# DPP rounds in sort networks and software-pipelined token-prep loads on top of id-paced pooled PEER
# speedup vs baseline: 1.1549x; 1.0051x over previous
.Lxp_sweep:
	v_readfirstlane_b32 s2, v58
	s_lshr_b32 s3, s23, 2
	s_lshl_b32 s3, s3, 6
	s_add_i32 s2, s2, s3
	s_and_b32 s3, s23, 3
	s_lshl_b32 s3, s3, 2
	s_add_i32 s2, s2, s3
	s_add_i32 s2, s2, s34
	s_sub_i32 s32, s2, 64
	s_lshl_b32 s2, s32, 11
	s_add_u32 s36, s92, s2
	s_addc_u32 s37, s93, 0
	s_mov_b32 s25, 0
	v_mov_b32_e32 v243, 0
	v_mov_b32_e32 v253, 0
	s_mov_b32 s2, s32
	s_lshl_b32 s3, s2, 11
	v_lshl_add_u32 v249, v60, 5, s3
	global_load_dwordx4 v[44:47], v249, s[16:17] offset:16
	global_load_dwordx4 v[48:51], v249, s[16:17]
	s_lshl_b32 s3, s2, 9
	v_lshl_add_u32 v250, v60, 2, s3
	global_load_dword v52, v250, s[12:13]
	global_load_dword v53, v250, s[12:13] offset:256
	global_load_dword v54, v250, s[14:15]
	global_load_dword v55, v250, s[14:15] offset:256
	s_lshl_b32 s2, s2, 2
	s_add_u32 s2, s41, s2
	s_addc_u32 s3, s43, 0
	global_load_dword v32, v253, s[2:3]
.Lxp_tok:
	s_waitcnt vmcnt(0)
	v_mov_b32_e32 v0, v44
	v_mov_b32_e32 v1, v45
	v_mov_b32_e32 v2, v46
	v_mov_b32_e32 v3, v47
	v_mov_b32_e32 v4, v48
	v_mov_b32_e32 v5, v49
	v_mov_b32_e32 v6, v50
	v_mov_b32_e32 v7, v51
	v_mov_b32_e32 v59, v52
	v_mov_b32_e32 v89, v53
	v_mov_b32_e32 v128, v54
	v_mov_b32_e32 v129, v55
	v_mov_b32_e32 v40, v32
	s_add_i32 s2, s25, 1
	s_min_u32 s2, s2, 3
	s_add_i32 s2, s32, s2
	s_lshl_b32 s3, s2, 11
	v_lshl_add_u32 v249, v60, 5, s3
	global_load_dwordx4 v[44:47], v249, s[16:17] offset:16
	global_load_dwordx4 v[48:51], v249, s[16:17]
	s_lshl_b32 s3, s2, 9
	v_lshl_add_u32 v250, v60, 2, s3
	global_load_dword v52, v250, s[12:13]
	global_load_dword v53, v250, s[12:13] offset:256
	global_load_dword v54, v250, s[14:15]
	global_load_dword v55, v250, s[14:15] offset:256
	s_lshl_b32 s2, s2, 2
	s_add_u32 s2, s41, s2
	s_addc_u32 s3, s43, 0
	global_load_dword v32, v253, s[2:3]
	s_lshl_b32 s2, s25, 12
	v_add_u32_e32 v251, s2, v248
	v_mov_b32_e32 v8, 0
	v_mov_b32_e32 v9, 0
	v_mov_b32_e32 v10, 0
	v_mov_b32_e32 v11, 0
	ds_write_b128 v251, v[8:11]
	ds_write_b128 v251, v[8:11] offset:1024
	ds_write_b128 v251, v[8:11] offset:2048
	ds_write_b128 v251, v[8:11] offset:3072
	v_lshlrev_b32_e32 v84, 16, v4
	v_and_b32_e32 v85, 0xffff0000, v4
	v_lshlrev_b32_e32 v86, 16, v5
	v_and_b32_e32 v87, 0xffff0000, v5
	v_lshlrev_b32_e32 v80, 16, v6
	v_and_b32_e32 v81, 0xffff0000, v6
	v_lshlrev_b32_e32 v82, 16, v7
	v_and_b32_e32 v83, 0xffff0000, v7
	v_lshlrev_b32_e32 v76, 16, v0
	v_and_b32_e32 v77, 0xffff0000, v0
	v_lshlrev_b32_e32 v78, 16, v1
	v_and_b32_e32 v79, 0xffff0000, v1
	v_lshlrev_b32_e32 v72, 16, v2
	v_and_b32_e32 v73, 0xffff0000, v2
	v_lshlrev_b32_e32 v74, 16, v3
	v_and_b32_e32 v75, 0xffff0000, v3
	v_max3_f32 v0, |v84|, 0, |v85|
	v_max3_f32 v0, v0, |v86|, |v87|
	v_max3_f32 v0, v0, |v80|, |v81|
	v_max3_f32 v0, v0, |v82|, |v83|
	v_max3_f32 v0, v0, |v76|, |v77|
	v_max3_f32 v0, v0, |v78|, |v79|
	v_max3_f32 v0, v0, |v72|, |v73|
	v_max3_f32 v0, v0, |v74|, |v75|
	ds_bpermute_b32 v1, v127, v0
	s_waitcnt lgkmcnt(0)
	v_max_f32_e32 v1, v1, v1
	v_max_f32_e32 v0, v0, v1
	ds_bpermute_b32 v1, v126, v0
	s_waitcnt lgkmcnt(0)
	v_max_f32_e32 v1, v1, v1
	v_max_f32_e32 v0, v0, v1
	ds_bpermute_b32 v1, v125, v0
	s_waitcnt lgkmcnt(0)
	v_max_f32_e32 v1, v1, v1
	v_max_f32_e32 v0, v0, v1
	ds_bpermute_b32 v1, v124, v0
	s_waitcnt lgkmcnt(0)
	v_max_f32_e32 v1, v1, v1
	v_max_f32_e32 v0, v0, v1
	ds_bpermute_b32 v1, v123, v0
	s_waitcnt lgkmcnt(0)
	v_max_f32_e32 v1, v1, v1
	v_max_f32_e32 v0, v0, v1
	ds_bpermute_b32 v1, v122, v0
	s_waitcnt lgkmcnt(0)
	v_max_f32_e32 v1, v1, v1
	v_max_f32_e32 v0, v0, v1
	v_max_f32_e32 v16, s63, v0
	v_div_scale_f32 v17, s[2:3], v16, v16, s64
	v_rcp_f32_e32 v18, v17
	s_nop 0
	v_fma_f32 v8, -v17, v18, 1.0
	v_fmac_f32_e32 v18, v8, v18
	v_div_scale_f32 v8, vcc, s64, v16, s64
	v_mul_f32_e32 v9, v8, v18
	v_fma_f32 v10, -v17, v9, v8
	v_fmac_f32_e32 v9, v10, v18
	v_fma_f32 v8, -v17, v9, v8
	s_nop 0
	v_div_fmas_f32 v8, v8, v18, v9
	v_div_fixup_f32 v41, v8, v16, s64
	v_mul_f32_e32 v42, 0x3c010204, v16
	v_mul_f32_e32 v43, v40, v42
	v_cmp_eq_u32_e32 vcc, s25, v60
	s_nop 1
	v_cndmask_b32_e32 v244, v244, v43, vcc
	v_mul_f32_e32 v8, v41, v84
	v_rndne_f32_e32 v8, v8
	v_cvt_i32_f32_e32 v8, v8
	v_mul_f32_e32 v9, v41, v85
	v_rndne_f32_e32 v9, v9
	v_cvt_i32_f32_e32 v9, v9
	v_mul_f32_e32 v10, v41, v86
	v_rndne_f32_e32 v10, v10
	v_cvt_i32_f32_e32 v10, v10
	v_mul_f32_e32 v11, v41, v87
	v_rndne_f32_e32 v11, v11
	v_cvt_i32_f32_e32 v11, v11
	v_and_b32_e32 v8, 0xff, v8
	v_and_b32_e32 v9, 0xff, v9
	v_and_b32_e32 v10, 0xff, v10
	v_lshl_or_b32 v8, v9, 8, v8
	v_lshl_or_b32 v8, v10, 16, v8
	v_lshl_or_b32 v133, v11, 24, v8
	v_mul_f32_e32 v8, v41, v80
	v_rndne_f32_e32 v8, v8
	v_cvt_i32_f32_e32 v8, v8
	v_mul_f32_e32 v9, v41, v81
	v_rndne_f32_e32 v9, v9
	v_cvt_i32_f32_e32 v9, v9
	v_mul_f32_e32 v10, v41, v82
	v_rndne_f32_e32 v10, v10
	v_cvt_i32_f32_e32 v10, v10
	v_mul_f32_e32 v11, v41, v83
	v_rndne_f32_e32 v11, v11
	v_cvt_i32_f32_e32 v11, v11
	v_and_b32_e32 v8, 0xff, v8
	v_and_b32_e32 v9, 0xff, v9
	v_and_b32_e32 v10, 0xff, v10
	v_lshl_or_b32 v8, v9, 8, v8
	v_lshl_or_b32 v8, v10, 16, v8
	v_lshl_or_b32 v134, v11, 24, v8
	v_mul_f32_e32 v8, v41, v76
	v_rndne_f32_e32 v8, v8
	v_cvt_i32_f32_e32 v8, v8
	v_mul_f32_e32 v9, v41, v77
	v_rndne_f32_e32 v9, v9
	v_cvt_i32_f32_e32 v9, v9
	v_mul_f32_e32 v10, v41, v78
	v_rndne_f32_e32 v10, v10
	v_cvt_i32_f32_e32 v10, v10
	v_mul_f32_e32 v11, v41, v79
	v_rndne_f32_e32 v11, v11
	v_cvt_i32_f32_e32 v11, v11
	v_and_b32_e32 v8, 0xff, v8
	v_and_b32_e32 v9, 0xff, v9
	v_and_b32_e32 v10, 0xff, v10
	v_lshl_or_b32 v8, v9, 8, v8
	v_lshl_or_b32 v8, v10, 16, v8
	v_lshl_or_b32 v135, v11, 24, v8
	v_mul_f32_e32 v8, v41, v72
	v_rndne_f32_e32 v8, v8
	v_cvt_i32_f32_e32 v8, v8
	v_mul_f32_e32 v9, v41, v73
	v_rndne_f32_e32 v9, v9
	v_cvt_i32_f32_e32 v9, v9
	v_mul_f32_e32 v10, v41, v74
	v_rndne_f32_e32 v10, v10
	v_cvt_i32_f32_e32 v10, v10
	v_mul_f32_e32 v11, v41, v75
	v_rndne_f32_e32 v11, v11
	v_cvt_i32_f32_e32 v11, v11
	v_and_b32_e32 v8, 0xff, v8
	v_and_b32_e32 v9, 0xff, v9
	v_and_b32_e32 v10, 0xff, v10
	v_lshl_or_b32 v8, v9, 8, v8
	v_lshl_or_b32 v8, v10, 16, v8
	v_lshl_or_b32 v136, v11, 24, v8
	s_cmp_eq_u32 s25, 0
	s_cbranch_scc1 .Lxp_sxq0
	s_cmp_eq_u32 s25, 1
	s_cbranch_scc1 .Lxp_sxq1
	s_cmp_eq_u32 s25, 2
	s_cbranch_scc1 .Lxp_sxq2
	v_mov_b32_e32 v236, v133
	v_mov_b32_e32 v237, v134
	v_mov_b32_e32 v238, v135
	v_mov_b32_e32 v239, v136
	s_branch .Lxp_sxqd

.Lxp_sxqd:
	v_lshl_or_b32 v62, v59, 7, v60
	v_lshlrev_b32_e32 v63, 7, v89
	v_or3_b32 v63, v63, v60, 64
	s_nop 1
	v_mov_b32_dpp v64, v62 quad_perm:[1,0,3,2] row_mask:0xf bank_mask:0xf
	v_mov_b32_dpp v65, v63 quad_perm:[1,0,3,2] row_mask:0xf bank_mask:0xf
	s_mov_b32 vcc_lo, 0x99999999
	s_mov_b32 vcc_hi, 0x99999999
	v_min_u32_e32 v66, v62, v64
	v_max_u32_e32 v67, v62, v64
	v_min_u32_e32 v68, v63, v65
	v_max_u32_e32 v69, v63, v65
	v_cndmask_b32_e32 v62, v67, v66, vcc
	v_cndmask_b32_e32 v63, v69, v68, vcc
	s_nop 1
	v_mov_b32_dpp v64, v62 quad_perm:[2,3,0,1] row_mask:0xf bank_mask:0xf
	v_mov_b32_dpp v65, v63 quad_perm:[2,3,0,1] row_mask:0xf bank_mask:0xf
	s_mov_b32 vcc_lo, 0xc3c3c3c3
	s_mov_b32 vcc_hi, 0xc3c3c3c3
	v_min_u32_e32 v66, v62, v64
	v_max_u32_e32 v67, v62, v64
	v_min_u32_e32 v68, v63, v65
	v_max_u32_e32 v69, v63, v65
	v_cndmask_b32_e32 v62, v67, v66, vcc
	v_cndmask_b32_e32 v63, v69, v68, vcc
	s_nop 1
	v_mov_b32_dpp v64, v62 quad_perm:[1,0,3,2] row_mask:0xf bank_mask:0xf
	v_mov_b32_dpp v65, v63 quad_perm:[1,0,3,2] row_mask:0xf bank_mask:0xf
	s_mov_b32 vcc_lo, 0xa5a5a5a5
	s_mov_b32 vcc_hi, 0xa5a5a5a5
	v_min_u32_e32 v66, v62, v64
	v_max_u32_e32 v67, v62, v64
	v_min_u32_e32 v68, v63, v65
	v_max_u32_e32 v69, v63, v65
	v_cndmask_b32_e32 v62, v67, v66, vcc
	v_cndmask_b32_e32 v63, v69, v68, vcc
	ds_bpermute_b32 v64, v124, v62
	ds_bpermute_b32 v65, v124, v63
	s_mov_b32 vcc_lo, 0xf00ff00f
	s_mov_b32 vcc_hi, 0xf00ff00f
	s_waitcnt lgkmcnt(0)
	v_min_u32_e32 v66, v62, v64
	v_max_u32_e32 v67, v62, v64
	v_min_u32_e32 v68, v63, v65
	v_max_u32_e32 v69, v63, v65
	v_cndmask_b32_e32 v62, v67, v66, vcc
	v_cndmask_b32_e32 v63, v69, v68, vcc
	s_nop 1
	v_mov_b32_dpp v64, v62 quad_perm:[2,3,0,1] row_mask:0xf bank_mask:0xf
	v_mov_b32_dpp v65, v63 quad_perm:[2,3,0,1] row_mask:0xf bank_mask:0xf
	s_mov_b32 vcc_lo, 0xcc33cc33
	s_mov_b32 vcc_hi, 0xcc33cc33
	v_min_u32_e32 v66, v62, v64
	v_max_u32_e32 v67, v62, v64
	v_min_u32_e32 v68, v63, v65
	v_max_u32_e32 v69, v63, v65
	v_cndmask_b32_e32 v62, v67, v66, vcc
	v_cndmask_b32_e32 v63, v69, v68, vcc
	s_nop 1
	v_mov_b32_dpp v64, v62 quad_perm:[1,0,3,2] row_mask:0xf bank_mask:0xf
	v_mov_b32_dpp v65, v63 quad_perm:[1,0,3,2] row_mask:0xf bank_mask:0xf
	s_mov_b32 vcc_lo, 0xaa55aa55
	s_mov_b32 vcc_hi, 0xaa55aa55
	v_min_u32_e32 v66, v62, v64
	v_max_u32_e32 v67, v62, v64
	v_min_u32_e32 v68, v63, v65
	v_max_u32_e32 v69, v63, v65
	v_cndmask_b32_e32 v62, v67, v66, vcc
	v_cndmask_b32_e32 v63, v69, v68, vcc
	s_nop 1
	v_mov_b32_dpp v64, v62 row_ror:8 row_mask:0xf bank_mask:0xf
	v_mov_b32_dpp v65, v63 row_ror:8 row_mask:0xf bank_mask:0xf
	s_mov_b32 vcc_lo, 0xff0000ff
	s_mov_b32 vcc_hi, 0xff0000ff
	v_min_u32_e32 v66, v62, v64
	v_max_u32_e32 v67, v62, v64
	v_min_u32_e32 v68, v63, v65
	v_max_u32_e32 v69, v63, v65
	v_cndmask_b32_e32 v62, v67, v66, vcc
	v_cndmask_b32_e32 v63, v69, v68, vcc
	ds_bpermute_b32 v64, v124, v62
	ds_bpermute_b32 v65, v124, v63
	s_mov_b32 vcc_lo, 0xf0f00f0f
	s_mov_b32 vcc_hi, 0xf0f00f0f
	s_waitcnt lgkmcnt(0)
	v_min_u32_e32 v66, v62, v64
	v_max_u32_e32 v67, v62, v64
	v_min_u32_e32 v68, v63, v65
	v_max_u32_e32 v69, v63, v65
	v_cndmask_b32_e32 v62, v67, v66, vcc
	v_cndmask_b32_e32 v63, v69, v68, vcc
	s_nop 1
	v_mov_b32_dpp v64, v62 quad_perm:[2,3,0,1] row_mask:0xf bank_mask:0xf
	v_mov_b32_dpp v65, v63 quad_perm:[2,3,0,1] row_mask:0xf bank_mask:0xf
	s_mov_b32 vcc_lo, 0xcccc3333
	s_mov_b32 vcc_hi, 0xcccc3333
	v_min_u32_e32 v66, v62, v64
	v_max_u32_e32 v67, v62, v64
	v_min_u32_e32 v68, v63, v65
	v_max_u32_e32 v69, v63, v65
	v_cndmask_b32_e32 v62, v67, v66, vcc
	v_cndmask_b32_e32 v63, v69, v68, vcc
	s_nop 1
	v_mov_b32_dpp v64, v62 quad_perm:[1,0,3,2] row_mask:0xf bank_mask:0xf
	v_mov_b32_dpp v65, v63 quad_perm:[1,0,3,2] row_mask:0xf bank_mask:0xf
	s_mov_b32 vcc_lo, 0xaaaa5555
	s_mov_b32 vcc_hi, 0xaaaa5555
	v_min_u32_e32 v66, v62, v64
	v_max_u32_e32 v67, v62, v64
	v_min_u32_e32 v68, v63, v65
	v_max_u32_e32 v69, v63, v65
	v_cndmask_b32_e32 v62, v67, v66, vcc
	v_cndmask_b32_e32 v63, v69, v68, vcc
	ds_bpermute_b32 v64, v126, v62
	ds_bpermute_b32 v65, v126, v63
	s_mov_b32 vcc_lo, 0x0000ffff
	s_mov_b32 vcc_hi, 0xffff0000
	s_waitcnt lgkmcnt(0)
	v_min_u32_e32 v66, v62, v64
	v_max_u32_e32 v67, v62, v64
	v_min_u32_e32 v68, v63, v65
	v_max_u32_e32 v69, v63, v65
	v_cndmask_b32_e32 v62, v67, v66, vcc
	v_cndmask_b32_e32 v63, v69, v68, vcc
	s_nop 1
	v_mov_b32_dpp v64, v62 row_ror:8 row_mask:0xf bank_mask:0xf
	v_mov_b32_dpp v65, v63 row_ror:8 row_mask:0xf bank_mask:0xf
	s_mov_b32 vcc_lo, 0x00ff00ff
	s_mov_b32 vcc_hi, 0xff00ff00
	v_min_u32_e32 v66, v62, v64
	v_max_u32_e32 v67, v62, v64
	v_min_u32_e32 v68, v63, v65
	v_max_u32_e32 v69, v63, v65
	v_cndmask_b32_e32 v62, v67, v66, vcc
	v_cndmask_b32_e32 v63, v69, v68, vcc
	ds_bpermute_b32 v64, v124, v62
	ds_bpermute_b32 v65, v124, v63
	s_mov_b32 vcc_lo, 0x0f0f0f0f
	s_mov_b32 vcc_hi, 0xf0f0f0f0
	s_waitcnt lgkmcnt(0)
	v_min_u32_e32 v66, v62, v64
	v_max_u32_e32 v67, v62, v64
	v_min_u32_e32 v68, v63, v65
	v_max_u32_e32 v69, v63, v65
	v_cndmask_b32_e32 v62, v67, v66, vcc
	v_cndmask_b32_e32 v63, v69, v68, vcc
	s_nop 1
	v_mov_b32_dpp v64, v62 quad_perm:[2,3,0,1] row_mask:0xf bank_mask:0xf
	v_mov_b32_dpp v65, v63 quad_perm:[2,3,0,1] row_mask:0xf bank_mask:0xf
	s_mov_b32 vcc_lo, 0x33333333
	s_mov_b32 vcc_hi, 0xcccccccc
	v_min_u32_e32 v66, v62, v64
	v_max_u32_e32 v67, v62, v64
	v_min_u32_e32 v68, v63, v65
	v_max_u32_e32 v69, v63, v65
	v_cndmask_b32_e32 v62, v67, v66, vcc
	v_cndmask_b32_e32 v63, v69, v68, vcc
	s_nop 1
	v_mov_b32_dpp v64, v62 quad_perm:[1,0,3,2] row_mask:0xf bank_mask:0xf
	v_mov_b32_dpp v65, v63 quad_perm:[1,0,3,2] row_mask:0xf bank_mask:0xf
	s_mov_b32 vcc_lo, 0x55555555
	s_mov_b32 vcc_hi, 0xaaaaaaaa
	v_min_u32_e32 v66, v62, v64
	v_max_u32_e32 v67, v62, v64
	v_min_u32_e32 v68, v63, v65
	v_max_u32_e32 v69, v63, v65
	v_cndmask_b32_e32 v62, v67, v66, vcc
	v_cndmask_b32_e32 v63, v69, v68, vcc
	ds_bpermute_b32 v64, v127, v62
	ds_bpermute_b32 v65, v127, v63
	s_mov_b32 vcc_lo, 0xffffffff
	s_mov_b32 vcc_hi, 0x00000000
	s_waitcnt lgkmcnt(0)
	v_min_u32_e32 v66, v62, v64
	v_max_u32_e32 v67, v62, v64
	v_min_u32_e32 v68, v63, v65
	v_max_u32_e32 v69, v63, v65
	v_cndmask_b32_e32 v62, v67, v66, vcc
	v_cndmask_b32_e32 v63, v68, v69, vcc
	ds_bpermute_b32 v64, v126, v62
	ds_bpermute_b32 v65, v126, v63
	s_mov_b32 vcc_lo, 0x0000ffff
	s_mov_b32 vcc_hi, 0x0000ffff
	s_waitcnt lgkmcnt(0)
	v_min_u32_e32 v66, v62, v64
	v_max_u32_e32 v67, v62, v64
	v_min_u32_e32 v68, v63, v65
	v_max_u32_e32 v69, v63, v65
	v_cndmask_b32_e32 v62, v67, v66, vcc
	v_cndmask_b32_e32 v63, v68, v69, vcc
	s_nop 1
	v_mov_b32_dpp v64, v62 row_ror:8 row_mask:0xf bank_mask:0xf
	v_mov_b32_dpp v65, v63 row_ror:8 row_mask:0xf bank_mask:0xf
	s_mov_b32 vcc_lo, 0x00ff00ff
	s_mov_b32 vcc_hi, 0x00ff00ff
	v_min_u32_e32 v66, v62, v64
	v_max_u32_e32 v67, v62, v64
	v_min_u32_e32 v68, v63, v65
	v_max_u32_e32 v69, v63, v65
	v_cndmask_b32_e32 v62, v67, v66, vcc
	v_cndmask_b32_e32 v63, v68, v69, vcc
	ds_bpermute_b32 v64, v124, v62
	ds_bpermute_b32 v65, v124, v63
	s_mov_b32 vcc_lo, 0x0f0f0f0f
	s_mov_b32 vcc_hi, 0x0f0f0f0f
	s_waitcnt lgkmcnt(0)
	v_min_u32_e32 v66, v62, v64
	v_max_u32_e32 v67, v62, v64
	v_min_u32_e32 v68, v63, v65
	v_max_u32_e32 v69, v63, v65
	v_cndmask_b32_e32 v62, v67, v66, vcc
	v_cndmask_b32_e32 v63, v68, v69, vcc
	s_nop 1
	v_mov_b32_dpp v64, v62 quad_perm:[2,3,0,1] row_mask:0xf bank_mask:0xf
	v_mov_b32_dpp v65, v63 quad_perm:[2,3,0,1] row_mask:0xf bank_mask:0xf
	s_mov_b32 vcc_lo, 0x33333333
	s_mov_b32 vcc_hi, 0x33333333
	v_min_u32_e32 v66, v62, v64
	v_max_u32_e32 v67, v62, v64
	v_min_u32_e32 v68, v63, v65
	v_max_u32_e32 v69, v63, v65
	v_cndmask_b32_e32 v62, v67, v66, vcc
	v_cndmask_b32_e32 v63, v68, v69, vcc
	s_nop 1
	v_mov_b32_dpp v64, v62 quad_perm:[1,0,3,2] row_mask:0xf bank_mask:0xf
	v_mov_b32_dpp v65, v63 quad_perm:[1,0,3,2] row_mask:0xf bank_mask:0xf
	s_mov_b32 vcc_lo, 0x55555555
	s_mov_b32 vcc_hi, 0x55555555
	v_min_u32_e32 v66, v62, v64
	v_max_u32_e32 v67, v62, v64
	v_min_u32_e32 v68, v63, v65
	v_max_u32_e32 v69, v63, v65
	v_cndmask_b32_e32 v62, v67, v66, vcc
	v_cndmask_b32_e32 v63, v68, v69, vcc
	v_min_u32_e32 v66, v62, v63
	v_max_u32_e32 v63, v62, v63
	v_mov_b32_e32 v62, v66
	ds_bpermute_b32 v64, v127, v62
	ds_bpermute_b32 v65, v127, v63
	s_mov_b32 vcc_lo, 0xffffffff
	s_mov_b32 vcc_hi, 0x00000000
	s_waitcnt lgkmcnt(0)
	v_min_u32_e32 v66, v62, v64
	v_max_u32_e32 v67, v62, v64
	v_min_u32_e32 v68, v63, v65
	v_max_u32_e32 v69, v63, v65
	v_cndmask_b32_e32 v62, v67, v66, vcc
	v_cndmask_b32_e32 v63, v69, v68, vcc
	ds_bpermute_b32 v64, v126, v62
	ds_bpermute_b32 v65, v126, v63
	s_mov_b32 vcc_lo, 0x0000ffff
	s_mov_b32 vcc_hi, 0x0000ffff
	s_waitcnt lgkmcnt(0)
	v_min_u32_e32 v66, v62, v64
	v_max_u32_e32 v67, v62, v64
	v_min_u32_e32 v68, v63, v65
	v_max_u32_e32 v69, v63, v65
	v_cndmask_b32_e32 v62, v67, v66, vcc
	v_cndmask_b32_e32 v63, v69, v68, vcc
	s_nop 1
	v_mov_b32_dpp v64, v62 row_ror:8 row_mask:0xf bank_mask:0xf
	v_mov_b32_dpp v65, v63 row_ror:8 row_mask:0xf bank_mask:0xf
	s_mov_b32 vcc_lo, 0x00ff00ff
	s_mov_b32 vcc_hi, 0x00ff00ff
	v_min_u32_e32 v66, v62, v64
	v_max_u32_e32 v67, v62, v64
	v_min_u32_e32 v68, v63, v65
	v_max_u32_e32 v69, v63, v65
	v_cndmask_b32_e32 v62, v67, v66, vcc
	v_cndmask_b32_e32 v63, v69, v68, vcc
	ds_bpermute_b32 v64, v124, v62
	ds_bpermute_b32 v65, v124, v63
	s_mov_b32 vcc_lo, 0x0f0f0f0f
	s_mov_b32 vcc_hi, 0x0f0f0f0f
	s_waitcnt lgkmcnt(0)
	v_min_u32_e32 v66, v62, v64
	v_max_u32_e32 v67, v62, v64
	v_min_u32_e32 v68, v63, v65
	v_max_u32_e32 v69, v63, v65
	v_cndmask_b32_e32 v62, v67, v66, vcc
	v_cndmask_b32_e32 v63, v69, v68, vcc
	s_nop 1
	v_mov_b32_dpp v64, v62 quad_perm:[2,3,0,1] row_mask:0xf bank_mask:0xf
	v_mov_b32_dpp v65, v63 quad_perm:[2,3,0,1] row_mask:0xf bank_mask:0xf
	s_mov_b32 vcc_lo, 0x33333333
	s_mov_b32 vcc_hi, 0x33333333
	v_min_u32_e32 v66, v62, v64
	v_max_u32_e32 v67, v62, v64
	v_min_u32_e32 v68, v63, v65
	v_max_u32_e32 v69, v63, v65
	v_cndmask_b32_e32 v62, v67, v66, vcc
	v_cndmask_b32_e32 v63, v69, v68, vcc
	s_nop 1
	v_mov_b32_dpp v64, v62 quad_perm:[1,0,3,2] row_mask:0xf bank_mask:0xf
	v_mov_b32_dpp v65, v63 quad_perm:[1,0,3,2] row_mask:0xf bank_mask:0xf
	s_mov_b32 vcc_lo, 0x55555555
	s_mov_b32 vcc_hi, 0x55555555
	v_min_u32_e32 v66, v62, v64
	v_max_u32_e32 v67, v62, v64
	v_min_u32_e32 v68, v63, v65
	v_max_u32_e32 v69, v63, v65
	v_cndmask_b32_e32 v62, v67, v66, vcc
	v_cndmask_b32_e32 v63, v69, v68, vcc
	v_lshrrev_b32_e32 v250, 7, v62
	v_lshrrev_b32_e32 v88, 7, v63
	v_and_b32_e32 v64, 63, v62
	v_lshlrev_b32_e32 v64, 2, v64
	v_and_b32_e32 v65, 63, v63
	v_lshlrev_b32_e32 v65, 2, v65
	ds_bpermute_b32 v66, v64, v128
	ds_bpermute_b32 v67, v64, v129
	ds_bpermute_b32 v68, v65, v128
	ds_bpermute_b32 v69, v65, v129
	v_and_b32_e32 v70, 64, v62
	v_and_b32_e32 v71, 64, v63
	s_waitcnt lgkmcnt(0)
	v_cmp_eq_u32_e32 vcc, 0, v70
	s_nop 1
	v_cndmask_b32_e32 v251, v67, v66, vcc
	v_cmp_eq_u32_e32 vcc, 0, v71
	s_nop 1
	v_cndmask_b32_e32 v89, v69, v68, vcc
	s_add_i32 s2, s32, s25
	s_lshl_b32 s2, s2, 11
	v_lshl_add_u32 v249, v60, 3, s2
	global_store_dwordx2 v249, v[250:251], s[92:93]
	global_store_dwordx2 v249, v[88:89], s[92:93] offset:512
	v_and_b32_e32 v252, 15, v60
	v_lshlrev_b32_e32 v252, 4, v252
	ds_bpermute_b32 v64, v252, v250
	ds_bpermute_b32 v65, v252, v88
	s_mov_b32 vcc_lo, 0xffff0000
	s_mov_b32 vcc_hi, 0xffff0000
	s_waitcnt lgkmcnt(0)
	v_cndmask_b32_e32 v64, v64, v65, vcc
	v_and_b32_e32 v65, 31, v60
	s_lshl_b32 s2, s25, 5
	v_or_b32_e32 v65, s2, v65
	v_lshl_or_b32 v64, v64, 7, v65
	s_cmp_eq_u32 s25, 0
	s_cbranch_scc1 .Lxp_uk0
	s_cmp_eq_u32 s25, 1
	s_cbranch_scc1 .Lxp_uk1
	s_cmp_eq_u32 s25, 2
	s_cbranch_scc1 .Lxp_uk2
	s_mov_b32 vcc_lo, 0
	s_mov_b32 vcc_hi, -1
	s_nop 0
	v_cndmask_b32_e32 v241, v241, v64, vcc
	s_branch .Lxp_ukd

.Lxp_ukd:
	s_add_i32 s25, s25, 1
	s_cmp_lt_u32 s25, 4
	s_cbranch_scc1 .Lxp_tok
	s_waitcnt vmcnt(0)
	global_load_dword v70, v[246:247], off sc1
	s_nop 1
	v_mov_b32_dpp v64, v240 quad_perm:[1,0,3,2] row_mask:0xf bank_mask:0xf
	v_mov_b32_dpp v65, v241 quad_perm:[1,0,3,2] row_mask:0xf bank_mask:0xf
	s_mov_b32 vcc_lo, 0x99999999
	s_mov_b32 vcc_hi, 0x99999999
	v_min_u32_e32 v66, v240, v64
	v_max_u32_e32 v67, v240, v64
	v_min_u32_e32 v68, v241, v65
	v_max_u32_e32 v69, v241, v65
	v_cndmask_b32_e32 v240, v67, v66, vcc
	v_cndmask_b32_e32 v241, v69, v68, vcc
	s_nop 1
	v_mov_b32_dpp v64, v240 quad_perm:[2,3,0,1] row_mask:0xf bank_mask:0xf
	v_mov_b32_dpp v65, v241 quad_perm:[2,3,0,1] row_mask:0xf bank_mask:0xf
	s_mov_b32 vcc_lo, 0xc3c3c3c3
	s_mov_b32 vcc_hi, 0xc3c3c3c3
	v_min_u32_e32 v66, v240, v64
	v_max_u32_e32 v67, v240, v64
	v_min_u32_e32 v68, v241, v65
	v_max_u32_e32 v69, v241, v65
	v_cndmask_b32_e32 v240, v67, v66, vcc
	v_cndmask_b32_e32 v241, v69, v68, vcc
	s_nop 1
	v_mov_b32_dpp v64, v240 quad_perm:[1,0,3,2] row_mask:0xf bank_mask:0xf
	v_mov_b32_dpp v65, v241 quad_perm:[1,0,3,2] row_mask:0xf bank_mask:0xf
	s_mov_b32 vcc_lo, 0xa5a5a5a5
	s_mov_b32 vcc_hi, 0xa5a5a5a5
	v_min_u32_e32 v66, v240, v64
	v_max_u32_e32 v67, v240, v64
	v_min_u32_e32 v68, v241, v65
	v_max_u32_e32 v69, v241, v65
	v_cndmask_b32_e32 v240, v67, v66, vcc
	v_cndmask_b32_e32 v241, v69, v68, vcc
	ds_bpermute_b32 v64, v124, v240
	ds_bpermute_b32 v65, v124, v241
	s_mov_b32 vcc_lo, 0xf00ff00f
	s_mov_b32 vcc_hi, 0xf00ff00f
	s_waitcnt lgkmcnt(0)
	v_min_u32_e32 v66, v240, v64
	v_max_u32_e32 v67, v240, v64
	v_min_u32_e32 v68, v241, v65
	v_max_u32_e32 v69, v241, v65
	v_cndmask_b32_e32 v240, v67, v66, vcc
	v_cndmask_b32_e32 v241, v69, v68, vcc
	s_nop 1
	v_mov_b32_dpp v64, v240 quad_perm:[2,3,0,1] row_mask:0xf bank_mask:0xf
	v_mov_b32_dpp v65, v241 quad_perm:[2,3,0,1] row_mask:0xf bank_mask:0xf
	s_mov_b32 vcc_lo, 0xcc33cc33
	s_mov_b32 vcc_hi, 0xcc33cc33
	v_min_u32_e32 v66, v240, v64
	v_max_u32_e32 v67, v240, v64
	v_min_u32_e32 v68, v241, v65
	v_max_u32_e32 v69, v241, v65
	v_cndmask_b32_e32 v240, v67, v66, vcc
	v_cndmask_b32_e32 v241, v69, v68, vcc
	s_nop 1
	v_mov_b32_dpp v64, v240 quad_perm:[1,0,3,2] row_mask:0xf bank_mask:0xf
	v_mov_b32_dpp v65, v241 quad_perm:[1,0,3,2] row_mask:0xf bank_mask:0xf
	s_mov_b32 vcc_lo, 0xaa55aa55
	s_mov_b32 vcc_hi, 0xaa55aa55
	v_min_u32_e32 v66, v240, v64
	v_max_u32_e32 v67, v240, v64
	v_min_u32_e32 v68, v241, v65
	v_max_u32_e32 v69, v241, v65
	v_cndmask_b32_e32 v240, v67, v66, vcc
	v_cndmask_b32_e32 v241, v69, v68, vcc
	s_nop 1
	v_mov_b32_dpp v64, v240 row_ror:8 row_mask:0xf bank_mask:0xf
	v_mov_b32_dpp v65, v241 row_ror:8 row_mask:0xf bank_mask:0xf
	s_mov_b32 vcc_lo, 0xff0000ff
	s_mov_b32 vcc_hi, 0xff0000ff
	v_min_u32_e32 v66, v240, v64
	v_max_u32_e32 v67, v240, v64
	v_min_u32_e32 v68, v241, v65
	v_max_u32_e32 v69, v241, v65
	v_cndmask_b32_e32 v240, v67, v66, vcc
	v_cndmask_b32_e32 v241, v69, v68, vcc
	ds_bpermute_b32 v64, v124, v240
	ds_bpermute_b32 v65, v124, v241
	s_mov_b32 vcc_lo, 0xf0f00f0f
	s_mov_b32 vcc_hi, 0xf0f00f0f
	s_waitcnt lgkmcnt(0)
	v_min_u32_e32 v66, v240, v64
	v_max_u32_e32 v67, v240, v64
	v_min_u32_e32 v68, v241, v65
	v_max_u32_e32 v69, v241, v65
	v_cndmask_b32_e32 v240, v67, v66, vcc
	v_cndmask_b32_e32 v241, v69, v68, vcc
	s_nop 1
	v_mov_b32_dpp v64, v240 quad_perm:[2,3,0,1] row_mask:0xf bank_mask:0xf
	v_mov_b32_dpp v65, v241 quad_perm:[2,3,0,1] row_mask:0xf bank_mask:0xf
	s_mov_b32 vcc_lo, 0xcccc3333
	s_mov_b32 vcc_hi, 0xcccc3333
	v_min_u32_e32 v66, v240, v64
	v_max_u32_e32 v67, v240, v64
	v_min_u32_e32 v68, v241, v65
	v_max_u32_e32 v69, v241, v65
	v_cndmask_b32_e32 v240, v67, v66, vcc
	v_cndmask_b32_e32 v241, v69, v68, vcc
	s_nop 1
	v_mov_b32_dpp v64, v240 quad_perm:[1,0,3,2] row_mask:0xf bank_mask:0xf
	v_mov_b32_dpp v65, v241 quad_perm:[1,0,3,2] row_mask:0xf bank_mask:0xf
	s_mov_b32 vcc_lo, 0xaaaa5555
	s_mov_b32 vcc_hi, 0xaaaa5555
	v_min_u32_e32 v66, v240, v64
	v_max_u32_e32 v67, v240, v64
	v_min_u32_e32 v68, v241, v65
	v_max_u32_e32 v69, v241, v65
	v_cndmask_b32_e32 v240, v67, v66, vcc
	v_cndmask_b32_e32 v241, v69, v68, vcc
	ds_bpermute_b32 v64, v126, v240
	ds_bpermute_b32 v65, v126, v241
	s_mov_b32 vcc_lo, 0x0000ffff
	s_mov_b32 vcc_hi, 0xffff0000
	s_waitcnt lgkmcnt(0)
	v_min_u32_e32 v66, v240, v64
	v_max_u32_e32 v67, v240, v64
	v_min_u32_e32 v68, v241, v65
	v_max_u32_e32 v69, v241, v65
	v_cndmask_b32_e32 v240, v67, v66, vcc
	v_cndmask_b32_e32 v241, v69, v68, vcc
	s_nop 1
	v_mov_b32_dpp v64, v240 row_ror:8 row_mask:0xf bank_mask:0xf
	v_mov_b32_dpp v65, v241 row_ror:8 row_mask:0xf bank_mask:0xf
	s_mov_b32 vcc_lo, 0x00ff00ff
	s_mov_b32 vcc_hi, 0xff00ff00
	v_min_u32_e32 v66, v240, v64
	v_max_u32_e32 v67, v240, v64
	v_min_u32_e32 v68, v241, v65
	v_max_u32_e32 v69, v241, v65
	v_cndmask_b32_e32 v240, v67, v66, vcc
	v_cndmask_b32_e32 v241, v69, v68, vcc
	ds_bpermute_b32 v64, v124, v240
	ds_bpermute_b32 v65, v124, v241
	s_mov_b32 vcc_lo, 0x0f0f0f0f
	s_mov_b32 vcc_hi, 0xf0f0f0f0
	s_waitcnt lgkmcnt(0)
	v_min_u32_e32 v66, v240, v64
	v_max_u32_e32 v67, v240, v64
	v_min_u32_e32 v68, v241, v65
	v_max_u32_e32 v69, v241, v65
	v_cndmask_b32_e32 v240, v67, v66, vcc
	v_cndmask_b32_e32 v241, v69, v68, vcc
	s_nop 1
	v_mov_b32_dpp v64, v240 quad_perm:[2,3,0,1] row_mask:0xf bank_mask:0xf
	v_mov_b32_dpp v65, v241 quad_perm:[2,3,0,1] row_mask:0xf bank_mask:0xf
	s_mov_b32 vcc_lo, 0x33333333
	s_mov_b32 vcc_hi, 0xcccccccc
	v_min_u32_e32 v66, v240, v64
	v_max_u32_e32 v67, v240, v64
	v_min_u32_e32 v68, v241, v65
	v_max_u32_e32 v69, v241, v65
	v_cndmask_b32_e32 v240, v67, v66, vcc
	v_cndmask_b32_e32 v241, v69, v68, vcc
	s_nop 1
	v_mov_b32_dpp v64, v240 quad_perm:[1,0,3,2] row_mask:0xf bank_mask:0xf
	v_mov_b32_dpp v65, v241 quad_perm:[1,0,3,2] row_mask:0xf bank_mask:0xf
	s_mov_b32 vcc_lo, 0x55555555
	s_mov_b32 vcc_hi, 0xaaaaaaaa
	v_min_u32_e32 v66, v240, v64
	v_max_u32_e32 v67, v240, v64
	v_min_u32_e32 v68, v241, v65
	v_max_u32_e32 v69, v241, v65
	v_cndmask_b32_e32 v240, v67, v66, vcc
	v_cndmask_b32_e32 v241, v69, v68, vcc
	ds_bpermute_b32 v64, v127, v240
	ds_bpermute_b32 v65, v127, v241
	s_mov_b32 vcc_lo, 0xffffffff
	s_mov_b32 vcc_hi, 0x00000000
	s_waitcnt lgkmcnt(0)
	v_min_u32_e32 v66, v240, v64
	v_max_u32_e32 v67, v240, v64
	v_min_u32_e32 v68, v241, v65
	v_max_u32_e32 v69, v241, v65
	v_cndmask_b32_e32 v240, v67, v66, vcc
	v_cndmask_b32_e32 v241, v68, v69, vcc
	ds_bpermute_b32 v64, v126, v240
	ds_bpermute_b32 v65, v126, v241
	s_mov_b32 vcc_lo, 0x0000ffff
	s_mov_b32 vcc_hi, 0x0000ffff
	s_waitcnt lgkmcnt(0)
	v_min_u32_e32 v66, v240, v64
	v_max_u32_e32 v67, v240, v64
	v_min_u32_e32 v68, v241, v65
	v_max_u32_e32 v69, v241, v65
	v_cndmask_b32_e32 v240, v67, v66, vcc
	v_cndmask_b32_e32 v241, v68, v69, vcc
	s_nop 1
	v_mov_b32_dpp v64, v240 row_ror:8 row_mask:0xf bank_mask:0xf
	v_mov_b32_dpp v65, v241 row_ror:8 row_mask:0xf bank_mask:0xf
	s_mov_b32 vcc_lo, 0x00ff00ff
	s_mov_b32 vcc_hi, 0x00ff00ff
	v_min_u32_e32 v66, v240, v64
	v_max_u32_e32 v67, v240, v64
	v_min_u32_e32 v68, v241, v65
	v_max_u32_e32 v69, v241, v65
	v_cndmask_b32_e32 v240, v67, v66, vcc
	v_cndmask_b32_e32 v241, v68, v69, vcc
	ds_bpermute_b32 v64, v124, v240
	ds_bpermute_b32 v65, v124, v241
	s_mov_b32 vcc_lo, 0x0f0f0f0f
	s_mov_b32 vcc_hi, 0x0f0f0f0f
	s_waitcnt lgkmcnt(0)
	v_min_u32_e32 v66, v240, v64
	v_max_u32_e32 v67, v240, v64
	v_min_u32_e32 v68, v241, v65
	v_max_u32_e32 v69, v241, v65
	v_cndmask_b32_e32 v240, v67, v66, vcc
	v_cndmask_b32_e32 v241, v68, v69, vcc
	s_nop 1
	v_mov_b32_dpp v64, v240 quad_perm:[2,3,0,1] row_mask:0xf bank_mask:0xf
	v_mov_b32_dpp v65, v241 quad_perm:[2,3,0,1] row_mask:0xf bank_mask:0xf
	s_mov_b32 vcc_lo, 0x33333333
	s_mov_b32 vcc_hi, 0x33333333
	v_min_u32_e32 v66, v240, v64
	v_max_u32_e32 v67, v240, v64
	v_min_u32_e32 v68, v241, v65
	v_max_u32_e32 v69, v241, v65
	v_cndmask_b32_e32 v240, v67, v66, vcc
	v_cndmask_b32_e32 v241, v68, v69, vcc
	s_nop 1
	v_mov_b32_dpp v64, v240 quad_perm:[1,0,3,2] row_mask:0xf bank_mask:0xf
	v_mov_b32_dpp v65, v241 quad_perm:[1,0,3,2] row_mask:0xf bank_mask:0xf
	s_mov_b32 vcc_lo, 0x55555555
	s_mov_b32 vcc_hi, 0x55555555
	v_min_u32_e32 v66, v240, v64
	v_max_u32_e32 v67, v240, v64
	v_min_u32_e32 v68, v241, v65
	v_max_u32_e32 v69, v241, v65
	v_cndmask_b32_e32 v240, v67, v66, vcc
	v_cndmask_b32_e32 v241, v68, v69, vcc
	v_min_u32_e32 v66, v240, v241
	v_max_u32_e32 v241, v240, v241
	v_mov_b32_e32 v240, v66
	ds_bpermute_b32 v64, v127, v240
	ds_bpermute_b32 v65, v127, v241
	s_mov_b32 vcc_lo, 0xffffffff
	s_mov_b32 vcc_hi, 0x00000000
	s_waitcnt lgkmcnt(0)
	v_min_u32_e32 v66, v240, v64
	v_max_u32_e32 v67, v240, v64
	v_min_u32_e32 v68, v241, v65
	v_max_u32_e32 v69, v241, v65
	v_cndmask_b32_e32 v240, v67, v66, vcc
	v_cndmask_b32_e32 v241, v69, v68, vcc
	ds_bpermute_b32 v64, v126, v240
	ds_bpermute_b32 v65, v126, v241
	s_mov_b32 vcc_lo, 0x0000ffff
	s_mov_b32 vcc_hi, 0x0000ffff
	s_waitcnt lgkmcnt(0)
	v_min_u32_e32 v66, v240, v64
	v_max_u32_e32 v67, v240, v64
	v_min_u32_e32 v68, v241, v65
	v_max_u32_e32 v69, v241, v65
	v_cndmask_b32_e32 v240, v67, v66, vcc
	v_cndmask_b32_e32 v241, v69, v68, vcc
	s_nop 1
	v_mov_b32_dpp v64, v240 row_ror:8 row_mask:0xf bank_mask:0xf
	v_mov_b32_dpp v65, v241 row_ror:8 row_mask:0xf bank_mask:0xf
	s_mov_b32 vcc_lo, 0x00ff00ff
	s_mov_b32 vcc_hi, 0x00ff00ff
	v_min_u32_e32 v66, v240, v64
	v_max_u32_e32 v67, v240, v64
	v_min_u32_e32 v68, v241, v65
	v_max_u32_e32 v69, v241, v65
	v_cndmask_b32_e32 v240, v67, v66, vcc
	v_cndmask_b32_e32 v241, v69, v68, vcc
	ds_bpermute_b32 v64, v124, v240
	ds_bpermute_b32 v65, v124, v241
	s_mov_b32 vcc_lo, 0x0f0f0f0f
	s_mov_b32 vcc_hi, 0x0f0f0f0f
	s_waitcnt lgkmcnt(0)
	v_min_u32_e32 v66, v240, v64
	v_max_u32_e32 v67, v240, v64
	v_min_u32_e32 v68, v241, v65
	v_max_u32_e32 v69, v241, v65
	v_cndmask_b32_e32 v240, v67, v66, vcc
	v_cndmask_b32_e32 v241, v69, v68, vcc
	s_nop 1
	v_mov_b32_dpp v64, v240 quad_perm:[2,3,0,1] row_mask:0xf bank_mask:0xf
	v_mov_b32_dpp v65, v241 quad_perm:[2,3,0,1] row_mask:0xf bank_mask:0xf
	s_mov_b32 vcc_lo, 0x33333333
	s_mov_b32 vcc_hi, 0x33333333
	v_min_u32_e32 v66, v240, v64
	v_max_u32_e32 v67, v240, v64
	v_min_u32_e32 v68, v241, v65
	v_max_u32_e32 v69, v241, v65
	v_cndmask_b32_e32 v240, v67, v66, vcc
	v_cndmask_b32_e32 v241, v69, v68, vcc
	s_nop 1
	v_mov_b32_dpp v64, v240 quad_perm:[1,0,3,2] row_mask:0xf bank_mask:0xf
	v_mov_b32_dpp v65, v241 quad_perm:[1,0,3,2] row_mask:0xf bank_mask:0xf
	s_mov_b32 vcc_lo, 0x55555555
	s_mov_b32 vcc_hi, 0x55555555
	v_min_u32_e32 v66, v240, v64
	v_max_u32_e32 v67, v240, v64
	v_min_u32_e32 v68, v241, v65
	v_max_u32_e32 v69, v241, v65
	v_cndmask_b32_e32 v240, v67, v66, vcc
	v_cndmask_b32_e32 v241, v69, v68, vcc
	s_waitcnt vmcnt(0)
	v_readfirstlane_b32 s2, v70
	s_and_b32 s2, s2, 0x3fff
	s_mov_b32 s97, s2
	s_lshl_b32 s3, s2, 7
	v_cmp_gt_u32_e32 vcc, s3, v240
	s_nop 1
	s_bcnt1_i32_b64 s2, vcc
	v_cmp_gt_u32_e32 vcc, s3, v241
	s_nop 1
	s_bcnt1_i32_b64 s3, vcc
	s_add_i32 s2, s2, s3
	v_add_u32_e32 v64, s2, v60
	v_and_b32_e32 v64, 0x7f, v64
	v_and_b32_e32 v65, 63, v64
	v_lshlrev_b32_e32 v65, 2, v65
	ds_bpermute_b32 v66, v65, v240
	ds_bpermute_b32 v67, v65, v241
	v_cmp_gt_u32_e32 vcc, 64, v64
	s_waitcnt lgkmcnt(0)
	v_cndmask_b32_e32 v240, v67, v66, vcc
	v_cndmask_b32_e32 v241, v66, v67, vcc
	v_mov_b32_e32 v132, v70
	s_nop 1
	v_readlane_b32 s2, v240, 0
	s_and_b32 s3, s2, 31
	s_lshl_b32 s3, s3, 5
	s_bfe_u32 s94, s2, 0x20005
	s_lshl_b32 s2, s94, 11
	s_add_i32 s3, s3, s2
	s_load_dwordx8 s[84:91], s[36:37], s3
	s_waitcnt lgkmcnt(0)
	s_and_b32 s84, s84, 0x3fff
	s_lshl_b32 s2, s84, 11
	v_lshl_add_u32 v249, v60, 4, s2
	global_load_dwordx4 v[8:11], v249, s[18:19]
	global_load_dwordx4 v[40:43], v249, s[20:21]
	s_lshl_b32 s2, s84, 2
	v_writelane_b32 v147, s2, 0
	v_writelane_b32 v0, s85, 0
	s_and_b32 s86, s86, 0x3fff
	s_lshl_b32 s2, s86, 11
	v_lshl_add_u32 v249, v60, 4, s2
	global_load_dwordx4 v[16:19], v249, s[18:19]
	global_load_dwordx4 v[44:47], v249, s[20:21]
	s_lshl_b32 s2, s86, 2
	v_writelane_b32 v147, s2, 1
	v_writelane_b32 v0, s87, 1
	s_and_b32 s88, s88, 0x3fff
	s_lshl_b32 s2, s88, 11
	v_lshl_add_u32 v249, v60, 4, s2
	global_load_dwordx4 v[32:35], v249, s[18:19]
	global_load_dwordx4 v[48:51], v249, s[20:21]
	s_lshl_b32 s2, s88, 2
	v_writelane_b32 v147, s2, 2
	v_writelane_b32 v0, s89, 2
	s_and_b32 s90, s90, 0x3fff
	s_lshl_b32 s2, s90, 11
	v_lshl_add_u32 v249, v60, 4, s2
	global_load_dwordx4 v[36:39], v249, s[18:19]
	global_load_dwordx4 v[52:55], v249, s[20:21]
	s_lshl_b32 s2, s90, 2
	v_writelane_b32 v147, s2, 3
	v_writelane_b32 v0, s91, 3
	global_load_dword v138, v147, s[44:45]
	global_load_dword v139, v147, s[46:47]
	s_mov_b32 s33, s94
	v_readlane_b32 s2, v240, 1
	s_and_b32 s3, s2, 31
	s_lshl_b32 s3, s3, 5
	s_bfe_u32 s94, s2, 0x20005
	s_lshl_b32 s2, s94, 11
	s_add_i32 s3, s3, s2
	s_load_dwordx8 s[84:91], s[36:37], s3
	s_waitcnt lgkmcnt(0)
	s_and_b32 s84, s84, 0x3fff
	s_lshl_b32 s2, s84, 11
	v_lshl_add_u32 v249, v60, 4, s2
	global_load_dwordx4 v[152:155], v249, s[18:19]
	global_load_dwordx4 v[12:15], v249, s[20:21]
	s_lshl_b32 s2, s84, 2
	v_writelane_b32 v147, s2, 0
	v_writelane_b32 v1, s85, 0
	s_and_b32 s86, s86, 0x3fff
	s_lshl_b32 s2, s86, 11
	v_lshl_add_u32 v249, v60, 4, s2
	global_load_dwordx4 v[156:159], v249, s[18:19]
	global_load_dwordx4 v[20:23], v249, s[20:21]
	s_lshl_b32 s2, s86, 2
	v_writelane_b32 v147, s2, 1
	v_writelane_b32 v1, s87, 1
	s_and_b32 s88, s88, 0x3fff
	s_lshl_b32 s2, s88, 11
	v_lshl_add_u32 v249, v60, 4, s2
	global_load_dwordx4 v[160:163], v249, s[18:19]
	global_load_dwordx4 v[24:27], v249, s[20:21]
	s_lshl_b32 s2, s88, 2
	v_writelane_b32 v147, s2, 2
	v_writelane_b32 v1, s89, 2
	s_and_b32 s90, s90, 0x3fff
	s_lshl_b32 s2, s90, 11
	v_lshl_add_u32 v249, v60, 4, s2
	global_load_dwordx4 v[164:167], v249, s[18:19]
	global_load_dwordx4 v[28:31], v249, s[20:21]
	s_lshl_b32 s2, s90, 2
	v_writelane_b32 v147, s2, 3
	v_writelane_b32 v1, s91, 3
	global_load_dword v140, v147, s[44:45]
	global_load_dword v141, v147, s[46:47]
	s_mov_b32 s80, s94
	v_readlane_b32 s2, v240, 2
	s_and_b32 s3, s2, 31
	s_lshl_b32 s3, s3, 5
	s_bfe_u32 s94, s2, 0x20005
	s_lshl_b32 s2, s94, 11
	s_add_i32 s3, s3, s2
	s_load_dwordx8 s[84:91], s[36:37], s3
	s_mov_b32 s81, s94
	v_mov_b32_e32 v90, 0
	v_mov_b32_e32 v91, 0
	v_mov_b32_e32 v92, 0
	v_mov_b32_e32 v93, 0
	v_mov_b32_e32 v94, 0
	v_mov_b32_e32 v95, 0
	v_mov_b32_e32 v96, 0
	v_mov_b32_e32 v97, 0
	v_mov_b32_e32 v98, 0
	v_mov_b32_e32 v99, 0
	v_mov_b32_e32 v100, 0
	v_mov_b32_e32 v101, 0
	v_mov_b32_e32 v102, 0
	v_mov_b32_e32 v103, 0
	v_mov_b32_e32 v104, 0
	v_mov_b32_e32 v105, 0
	v_mov_b32_e32 v142, 0
	v_readlane_b32 s3, v244, s33
	s_nop 1
	v_mov_b32_e32 v137, s3
	s_cmp_eq_u32 s33, 0
	s_cbranch_scc1 .Lxp_ixq0
	s_cmp_eq_u32 s33, 1
	s_cbranch_scc1 .Lxp_ixq1
	s_cmp_eq_u32 s33, 2
	s_cbranch_scc1 .Lxp_ixq2
	v_mov_b32_e32 v133, v236
	v_mov_b32_e32 v134, v237
	v_mov_b32_e32 v135, v238
	v_mov_b32_e32 v136, v239
	s_branch .Lxp_ixqd
